# mlaprep row reduction: the 6-hop 64-lane butterfly uses v_permlane32/16_swap and DPP (same partners, same order) instead of ds_bpermute_b32 round trips
# baseline (speedup 1.0000x reference)
; __device__ __forceinline__ float bf2f(bf16_t v) { return __uint_as_float(((unsigned)v) << 16); }
; __device__ __forceinline__ float bflo(unsigned w) { return __uint_as_float(w << 16); }
; __device__ __forceinline__ float bfhi(unsigned w) { return __uint_as_float(w & 0xffff0000u); }
; __device__ void mlaprep_phase(const Params& p, int w0) {
;     ...
;   for (int r = blockIdx.x * 8 + wv; r < MTOT; r += gridDim.x * 8) {
;     const bf16_t* pr = p.P + (long)r * DIN;
;     const u32x2 cq = *(const u32x2*)(pr + MCQ + lane * 4);
;     const unsigned ck = *(const unsigned*)(pr + MCKV + lane * 2);
;     float sq = bflo(cq.x) * bflo(cq.x) + bfhi(cq.x) * bfhi(cq.x) + bflo(cq.y) * bflo(cq.y) + bfhi(cq.y) * bfhi(cq.y);
;     float sk = bflo(ck) * bflo(ck) + bfhi(ck) * bfhi(ck);
; #pragma unroll
;     for (int o = 32; o > 0; o >>= 1) { sq += __shfl_xor(sq, o); sk += __shfl_xor(sk, o); }
;     if (lane == 0) { p.rstd[2 * r] = rsqrtf(sq * (1.f / 256.f) + EPS); p.rstd[2 * r + 1] = rsqrtf(sk * (1.f / 128.f) + EPS); }
;     const float kv = bf2f(pr[MKR + (lane & 31)]);
;     float outv = kv; int b, key;
;     if (r < NLAT) {
;       b = r >> 11; key = r & 2047;
;       const float other = __shfl_xor(kv, 8);
;       const int i = lane & 7, part = (lane >> 4) & 1;
;       const float cs = p.ropetab[key * 32 + part * 16 + i], sn = p.ropetab[key * 32 + part * 16 + 8 + i];
.LBB0_929:
	v_readlane_b32 s16, v252, 20
	v_readlane_b32 s24, v252, 28
	v_readlane_b32 s25, v252, 29
	v_readlane_b32 s18, v252, 5
	v_readlane_b32 s19, v252, 6
	v_readlane_b32 s20, v251, 34
	s_movk_i32 s2, 0xf80
	v_mov_b32_e32 v7, v1
	v_mov_b32_e32 v9, v1
	v_mov_b64_e32 v[10:11], s[24:25]
	v_and_b32_e32 v188, 0x7ff, v16
	v_lshl_or_b32 v188, v188, 7, v23
	v_add_u32_e32 v192, s20, v16
	v_min_i32_e32 v192, 0x11fff, v192
	s_waitcnt vmcnt(2)
	v_mov_b64_e32 v[12:13], v[180:181]
	v_mov_b32_e32 v5, v182
	v_mov_b32_e32 v189, v183
	global_load_dword v190, v188, s[18:19] offset:32
	global_load_dword v191, v188, s[18:19]
	v_mad_i64_i32 v[184:185], s[8:9], v192, s2, v[10:11]
	v_lshl_add_u64 v[186:187], v[184:185], 0, v[0:1]
	global_load_dwordx2 v[180:181], v[186:187], off offset:3136
	v_lshl_add_u64 v[186:187], v[184:185], 0, v[6:7]
	global_load_dword v182, v[186:187], off offset:3648
	v_lshl_add_u64 v[186:187], v[184:185], 0, v[8:9]
	global_load_ushort v183, v[186:187], off offset:3904
	s_waitcnt lgkmcnt(0)
	v_readlane_b32 s17, v252, 21
	v_readlane_b32 s18, v252, 22
	v_readlane_b32 s19, v252, 23
	v_readlane_b32 s20, v252, 24
	v_readlane_b32 s21, v252, 25
	v_readlane_b32 s22, v252, 26
	v_readlane_b32 s23, v252, 27
	v_readlane_b32 s26, v252, 30
	v_readlane_b32 s27, v252, 31
	v_readlane_b32 s28, v252, 32
	v_readlane_b32 s29, v252, 33
	v_readlane_b32 s30, v252, 34
	v_readlane_b32 s31, v252, 35
	v_lshlrev_b32_e32 v15, 16, v13
	v_lshlrev_b32_e32 v14, 16, v12
	v_and_b32_e32 v7, 0xffff0000, v12
	v_pk_mul_f32 v[14:15], v[14:15], v[14:15]
	s_nop 0
	v_fma_f32 v7, v7, v7, v14
	v_add_f32_e32 v12, v15, v7
	v_lshlrev_b32_e32 v15, 16, v5
	v_and_b32_e32 v5, 0xffff0000, v5
	v_and_b32_e32 v14, 0xffff0000, v13
	v_mul_f32_e32 v13, v5, v5
	v_pk_fma_f32 v[12:13], v[14:15], v[14:15], v[12:13]
	v_mov_b32_e32 v14, v12
	v_mov_b32_e32 v15, v13
	s_nop 1
	v_permlane32_swap_b32_e32 v14, v12
	v_permlane32_swap_b32_e32 v15, v13
	v_pk_add_f32 v[12:13], v[12:13], v[14:15]
	v_mov_b32_e32 v14, v12
	v_mov_b32_e32 v15, v13
	s_nop 1
	v_permlane16_swap_b32_e32 v14, v12
	v_permlane16_swap_b32_e32 v15, v13
	v_pk_add_f32 v[12:13], v[12:13], v[14:15]
	s_nop 1
	v_add_f32_dpp v12, v12, v12 row_ror:8 row_mask:0xf bank_mask:0xf
	v_add_f32_dpp v13, v13, v13 row_ror:8 row_mask:0xf bank_mask:0xf
	s_nop 0
	v_mov_b32_dpp v14, v12 row_half_mirror row_mask:0xf bank_mask:0xf
	v_mov_b32_dpp v15, v13 row_half_mirror row_mask:0xf bank_mask:0xf
	s_nop 0
	v_add_f32_dpp v12, v14, v12 quad_perm:[3,2,1,0] row_mask:0xf bank_mask:0xf
	v_add_f32_dpp v13, v15, v13 quad_perm:[3,2,1,0] row_mask:0xf bank_mask:0xf
	s_nop 0
	v_add_f32_dpp v12, v12, v12 quad_perm:[2,3,0,1] row_mask:0xf bank_mask:0xf
	v_add_f32_dpp v13, v13, v13 quad_perm:[2,3,0,1] row_mask:0xf bank_mask:0xf
	s_nop 0
	v_add_f32_dpp v12, v12, v12 quad_perm:[1,0,3,2] row_mask:0xf bank_mask:0xf
	v_add_f32_dpp v13, v13, v13 quad_perm:[1,0,3,2] row_mask:0xf bank_mask:0xf
	s_and_saveexec_b64 s[14:15], vcc
	s_cbranch_execz .LBB0_931
	s_mov_b32 s8, 0x3b800000
	v_readlane_b32 s16, v253, 7
	s_waitcnt lgkmcnt(0)
	s_brev_b32 s9, 60
	v_mov_b32_e32 v14, 0x358637bd
	v_ashrrev_i32_e32 v5, 31, v4
	v_readlane_b32 s28, v253, 19
	v_readlane_b32 s29, v253, 20
	v_pk_fma_f32 v[12:13], v[12:13], s[8:9], v[14:15] op_sel_hi:[1,1,0]
	s_mov_b32 s2, 0x800000
	v_lshl_add_u64 v[24:25], v[4:5], 2, s[28:29]
	v_mul_f32_e32 v5, 0x4b800000, v12
	v_cmp_gt_f32_e64 s[10:11], s2, v12
	v_cmp_gt_f32_e64 s[8:9], s2, v13
	s_mov_b32 s2, 0x45800000
	v_cndmask_b32_e64 v5, v12, v5, s[10:11]
	v_rsq_f32_e32 v12, v5
	v_mul_f32_e32 v5, 0x4b800000, v13
	v_cndmask_b32_e64 v5, v13, v5, s[8:9]
	v_rsq_f32_e32 v13, v5
	v_readlane_b32 s17, v253, 8
	v_readlane_b32 s18, v253, 9
	v_readlane_b32 s19, v253, 10
	v_pk_mul_f32 v[14:15], v[12:13], s[2:3] op_sel_hi:[1,0]
	v_readlane_b32 s20, v253, 11
	v_cndmask_b32_e64 v13, v13, v15, s[8:9]
	v_cndmask_b32_e64 v12, v12, v14, s[10:11]
	v_readlane_b32 s21, v253, 12
	v_readlane_b32 s22, v253, 13
	v_readlane_b32 s23, v253, 14
	v_readlane_b32 s24, v253, 15
	v_readlane_b32 s25, v253, 16
	v_readlane_b32 s26, v253, 17
	v_readlane_b32 s27, v253, 18
	v_readlane_b32 s30, v253, 21
	v_readlane_b32 s31, v253, 22
	global_store_dwordx2 v[24:25], v[12:13], off
